# attention O stores: 16x dwordx2 -> 8x dwordx4 per lane via v_permlane32_swap (half the cache lines touched per unit)
# speedup vs baseline: 1.0115x; 1.0115x over previous
; DI unsigned pk2(float lo, float hi) { return pg8::cvt_pk_bf16(lo, hi); }
; DI void attn_unit(LAS unsigned char* lds, const bf16* P, bf16* OG, float* LSE, const float* relb, int u) {
;     ...
;     l += __shfl_xor(l, 32);
;     const float inv = 1.0f / l;
;     bf16* orow = OG + (size_t)g * ((size_t)TH * 512) + qtok * 512 + hs * 128;
; #pragma unroll
;     for (int dt = 0; dt < 4; ++dt)
; #pragma unroll
;         for (int rq = 0; rq < 4; ++rq) { v2u wv; wv.x = pk2(O[dt][4 * rq] * inv, O[dt][4 * rq + 1] * inv); wv.y = pk2(O[dt][4 * rq + 2] * inv, O[dt][4 * rq + 3] * inv);
;             *(v2u*)(orow + 32 * dt + 8 * rq + 4 * hh) = wv; }
;     if (hh == 0) LSE[qtok * 12 + head] = m * 0.6931471805599453f + __logf(l);
.LBB0_434:
	ds_bpermute_b32 v0, v184, v205
	s_ashr_i32 s7, s6, 31
	s_lshl_b64 s[6:7], s[6:7], 25
	s_add_u32 s6, s88, s6
	s_addc_u32 s7, s89, s7
	s_waitcnt lgkmcnt(0)
	v_add_f32_e32 v67, v205, v0
	v_div_scale_f32 v0, s[8:9], v67, v67, 1.0
	v_rcp_f32_e32 v68, v0
	s_and_b32 s5, s5, 0x180
	v_fma_f32 v69, -v0, v68, 1.0
	v_fmac_f32_e32 v68, v69, v68
	v_div_scale_f32 v69, vcc, 1.0, v67, 1.0
	v_mul_f32_e32 v70, v69, v68
	v_fma_f32 v71, -v0, v70, v69
	v_fmac_f32_e32 v70, v71, v68
	v_fma_f32 v0, -v0, v70, v69
	v_div_fmas_f32 v0, v0, v68, v70
	v_lshlrev_b64 v[68:69], 10, v[178:179]
	v_lshl_add_u64 v[68:69], s[6:7], 0, v[68:69]
	v_readlane_b32 s6, v254, 6
	v_readlane_b32 s7, v254, 7
	s_lshl_b32 s6, s5, 1
	v_div_fixup_f32 v70, v0, v67, 1.0
	v_lshl_add_u64 v[68:69], v[68:69], 0, s[6:7]
	v_lshlrev_b32_e32 v0, 1, v185
	v_lshl_add_u64 v[68:69], v[68:69], 0, v[0:1]
	v_lshrrev_b32_e32 v0, 5, v194
	v_lshlrev_b32_e32 v0, 3, v0
	v_lshl_add_u64 v[68:69], v[68:69], 0, v[0:1]
	v_mul_f32_e32 v0, v50, v70
	v_mul_f32_e32 v50, v51, v70
	v_cvt_pk_bf16_f32 v50, v0, v50
	v_mul_f32_e32 v0, v52, v70
	v_mul_f32_e32 v51, v53, v70
	v_cvt_pk_bf16_f32 v51, v0, v51
	v_mul_f32_e32 v0, v54, v70
	v_mul_f32_e32 v52, v55, v70
	v_cvt_pk_bf16_f32 v52, v0, v52
	v_mul_f32_e32 v0, v56, v70
	v_mul_f32_e32 v53, v57, v70
	v_cvt_pk_bf16_f32 v53, v0, v53
	s_nop 1
	v_permlane32_swap_b32_e32 v50, v52
	v_permlane32_swap_b32_e32 v51, v53
	global_store_dwordx4 v[68:69], v[50:53], off
	v_mul_f32_e32 v0, v58, v70
	v_mul_f32_e32 v58, v59, v70
	v_cvt_pk_bf16_f32 v58, v0, v58
	v_mul_f32_e32 v0, v60, v70
	v_mul_f32_e32 v59, v61, v70
	v_cvt_pk_bf16_f32 v59, v0, v59
	v_mul_f32_e32 v0, v62, v70
	v_mul_f32_e32 v60, v63, v70
	v_cvt_pk_bf16_f32 v60, v0, v60
	v_mul_f32_e32 v0, v64, v70
	v_mul_f32_e32 v61, v65, v70
	v_cvt_pk_bf16_f32 v61, v0, v61
	s_nop 1
	v_permlane32_swap_b32_e32 v58, v60
	v_permlane32_swap_b32_e32 v59, v61
	global_store_dwordx4 v[68:69], v[58:61], off offset:32
	v_mul_f32_e32 v0, v34, v70
	v_mul_f32_e32 v34, v35, v70
	v_cvt_pk_bf16_f32 v34, v0, v34
	v_mul_f32_e32 v0, v36, v70
	v_mul_f32_e32 v35, v37, v70
	v_cvt_pk_bf16_f32 v35, v0, v35
	v_mul_f32_e32 v0, v38, v70
	v_mul_f32_e32 v36, v39, v70
	v_cvt_pk_bf16_f32 v36, v0, v36
	v_mul_f32_e32 v0, v40, v70
	v_mul_f32_e32 v37, v41, v70
	v_cvt_pk_bf16_f32 v37, v0, v37
	s_nop 1
	v_permlane32_swap_b32_e32 v34, v36
	v_permlane32_swap_b32_e32 v35, v37
	global_store_dwordx4 v[68:69], v[34:37], off offset:64
	v_mul_f32_e32 v0, v42, v70
	v_mul_f32_e32 v42, v43, v70
	v_cvt_pk_bf16_f32 v42, v0, v42
	v_mul_f32_e32 v0, v44, v70
	v_mul_f32_e32 v43, v45, v70
	v_cvt_pk_bf16_f32 v43, v0, v43
	v_mul_f32_e32 v0, v46, v70
	v_mul_f32_e32 v44, v47, v70
	v_cvt_pk_bf16_f32 v44, v0, v44
	v_mul_f32_e32 v0, v48, v70
	v_mul_f32_e32 v45, v49, v70
	v_cvt_pk_bf16_f32 v45, v0, v45
	s_nop 1
	v_permlane32_swap_b32_e32 v42, v44
	v_permlane32_swap_b32_e32 v43, v45
	global_store_dwordx4 v[68:69], v[42:45], off offset:96
	v_mul_f32_e32 v0, v18, v70
	v_mul_f32_e32 v18, v19, v70
	v_cvt_pk_bf16_f32 v18, v0, v18
	v_mul_f32_e32 v0, v20, v70
	v_mul_f32_e32 v19, v21, v70
	v_cvt_pk_bf16_f32 v19, v0, v19
	v_mul_f32_e32 v0, v22, v70
	v_mul_f32_e32 v20, v23, v70
	v_cvt_pk_bf16_f32 v20, v0, v20
	v_mul_f32_e32 v0, v24, v70
	v_mul_f32_e32 v21, v25, v70
	v_cvt_pk_bf16_f32 v21, v0, v21
	s_nop 1
	v_permlane32_swap_b32_e32 v18, v20
	v_permlane32_swap_b32_e32 v19, v21
	global_store_dwordx4 v[68:69], v[18:21], off offset:128
	v_mul_f32_e32 v0, v26, v70
	v_mul_f32_e32 v26, v27, v70
	v_cvt_pk_bf16_f32 v26, v0, v26
	v_mul_f32_e32 v0, v28, v70
	v_mul_f32_e32 v27, v29, v70
	v_cvt_pk_bf16_f32 v27, v0, v27
	v_mul_f32_e32 v0, v30, v70
	v_mul_f32_e32 v28, v31, v70
	v_cvt_pk_bf16_f32 v28, v0, v28
	v_mul_f32_e32 v0, v32, v70
	v_mul_f32_e32 v29, v33, v70
	v_cvt_pk_bf16_f32 v29, v0, v29
	s_nop 1
	v_permlane32_swap_b32_e32 v26, v28
	v_permlane32_swap_b32_e32 v27, v29
	global_store_dwordx4 v[68:69], v[26:29], off offset:160
	v_mul_f32_e32 v0, v2, v70
	v_mul_f32_e32 v2, v3, v70
	v_cvt_pk_bf16_f32 v2, v0, v2
	v_mul_f32_e32 v0, v4, v70
	v_mul_f32_e32 v3, v5, v70
	v_cvt_pk_bf16_f32 v3, v0, v3
	v_mul_f32_e32 v0, v6, v70
	v_mul_f32_e32 v4, v7, v70
	v_cvt_pk_bf16_f32 v4, v0, v4
	v_mul_f32_e32 v0, v8, v70
	v_mul_f32_e32 v5, v9, v70
	v_cvt_pk_bf16_f32 v5, v0, v5
	s_nop 1
	v_permlane32_swap_b32_e32 v2, v4
	v_permlane32_swap_b32_e32 v3, v5
	global_store_dwordx4 v[68:69], v[2:5], off offset:192
	v_mul_f32_e32 v0, v10, v70
	v_mul_f32_e32 v10, v11, v70
	v_cvt_pk_bf16_f32 v10, v0, v10
	v_mul_f32_e32 v0, v12, v70
	v_mul_f32_e32 v11, v13, v70
	v_cvt_pk_bf16_f32 v11, v0, v11
	v_mul_f32_e32 v0, v14, v70
	v_mul_f32_e32 v12, v15, v70
	v_cvt_pk_bf16_f32 v12, v0, v12
	v_mul_f32_e32 v0, v16, v70
	v_mul_f32_e32 v13, v17, v70
	v_cvt_pk_bf16_f32 v13, v0, v13
	s_nop 1
	v_permlane32_swap_b32_e32 v10, v12
	v_permlane32_swap_b32_e32 v11, v13
	global_store_dwordx4 v[68:69], v[10:13], off offset:224
	s_mov_b32 s5, s7
	v_writelane_b32 v254, s4, 6
	s_nop 0
	v_writelane_b32 v254, s5, 7
	v_cmp_eq_u32_e32 vcc, 0, v183
	s_nop 1
	s_and_saveexec_b64 s[6:7], vcc
	s_cbranch_execz .LBB0_436
	s_mov_b32 s5, 0x800000
	v_cmp_gt_f32_e32 vcc, s5, v67
	s_mov_b32 s5, 0x3f317217
	s_nop 0
	v_cndmask_b32_e64 v0, 0, 32, vcc
	v_ldexp_f32 v0, v67, v0
	v_log_f32_e32 v0, v0
	v_cndmask_b32_e32 v2, 0, v195, vcc
	v_mul_f32_e32 v3, 0x3f317217, v0
	v_fma_f32 v3, v0, s5, -v3
	v_fmac_f32_e32 v3, 0x3377d1cf, v0
	s_mov_b32 s5, 0x7f800000
	v_fmac_f32_e32 v3, 0x3f317217, v0
	v_cmp_lt_f32_e64 vcc, |v0|, s5
	s_ashr_i32 s5, s4, 31
	s_nop 0
	v_cndmask_b32_e32 v0, v0, v3, vcc
	v_sub_f32_e32 v6, v0, v2
	v_mad_u64_u32 v[2:3], s[8:9], v178, 48, s[90:91]
	v_mov_b32_e32 v0, v3
	v_mad_u64_u32 v[4:5], s[8:9], v179, 48, v[0:1]
	v_mov_b32_e32 v3, v4
	v_fmac_f32_e32 v6, 0x3f317218, v66
	v_lshl_add_u64 v[2:3], s[4:5], 2, v[2:3]
	global_store_dword v[2:3], v6, off
